# P1 and P6 SwiGLU epilogues hand-written; ai=1 half interleaved into the next unit's first MFMA block, ai=0 half at the unit boundary
# baseline (speedup 1.0000x reference)
.LBB0_135:
	s_lshl_b32 s10, s71, 5
	s_and_b32 s37, s10, 0x60
	s_mov_b64 s[10:11], 0x80
	s_add_i32 m0, s47, 0x18000
	v_lshl_add_u64 v[6:7], v[6:7], 0, s[10:11]
	s_lshl_b32 s36, s1, 13
	s_lshr_b32 s38, s37, 3
	s_waitcnt vmcnt(2)
	s_barrier
	global_load_lds_dwordx4 v[6:7], off
	v_lshl_add_u64 v[4:5], v[4:5], 0, s[10:11]
	s_add_i32 m0, s47, 0x1a000
	s_add_i32 s69, s47, 0x8000
	s_add_i32 s70, s47, 0xa000
	global_load_lds_dwordx4 v[4:5], off
	v_lshl_add_u64 v[0:1], v[0:1], 0, s[10:11]
	s_mov_b32 m0, s69
	s_add_u32 s26, s50, 0x40080
	global_load_lds_dwordx4 v[0:1], off
	v_lshl_add_u64 v[0:1], v[2:3], 0, s[10:11]
	s_mov_b32 m0, s70
	s_addc_u32 s27, s51, 0
	global_load_lds_dwordx4 v[0:1], off
	s_add_i32 m0, s47, 0x1c000
	v_lshl_add_u64 v[0:1], s[26:27], 0, v[132:133]
	global_load_lds_dwordx4 v[0:1], off
	v_lshl_add_u64 v[0:1], s[26:27], 0, v[128:129]
	s_add_i32 m0, s47, 0x1e000
	v_lshrrev_b32_e32 v2, 6, v10
	global_load_lds_dwordx4 v[0:1], off
	v_and_b32_e32 v0, 15, v10
	v_lshlrev_b32_e32 v5, 2, v10
	v_lshl_or_b32 v144, s1, 6, v0
	v_and_b32_e32 v3, 48, v10
	v_lshlrev_b32_e32 v4, 10, v2
	v_lshlrev_b32_e32 v0, 6, v0
	v_and_b32_e32 v5, 32, v5
	v_or_b32_e32 v2, s38, v2
	v_bitop3_b32 v6, v0, v5, v3 bitop3:0x36
	v_or_b32_e32 v0, v0, v3
	v_lshlrev_b32_e32 v2, 10, v2
	v_lshrrev_b32_e32 v1, 1, v10
	v_bitop3_b32 v145, v0, v2, v5 bitop3:0xde
	v_lshlrev_b32_e32 v0, 14, v12
	v_and_b32_e32 v1, 56, v1
	v_and_b32_e32 v0, 0xffff8000, v0
	v_add_u32_e32 v146, s37, v1
	v_lshl_add_u32 v0, v13, 11, v0
	v_and_b32_e32 v1, 1, v12
	v_lshl_or_b32 v0, v1, 6, v0
	v_lshl_add_u32 v136, v14, 1, v0
	v_lshlrev_b32_e32 v0, 14, v8
	v_and_b32_e32 v0, 0xffff8000, v0
	s_waitcnt vmcnt(6)
	s_cmpk_lt_u32 s3, 0x100
	v_lshl_add_u32 v0, v9, 11, v0
	v_and_b32_e32 v1, 1, v8
	v_or3_b32 v4, v4, s36, v6
	s_cselect_b64 s[26:27], -1, 0
	v_lshl_or_b32 v0, v1, 6, v0
	s_add_i32 s73, 0, 0x10000
	s_add_i32 s74, 0, 0x14000
	s_sext_i32_i16 s76, s0
	s_ashr_i32 s71, s34, 31
	s_mov_b32 s72, s34
	v_mov_b32_e32 v137, v133
	v_lshl_add_u32 v138, v11, 1, v0
	v_mov_b32_e32 v139, v133
	v_mov_b64_e32 v[140:141], 0x1b80
	v_mov_b64_e32 v[142:143], 0x1b7f
	v_add_u32_e32 v147, s73, v145
	v_add_u32_e32 v148, s74, v145
	v_add_u32_e32 v149, 0, v4
	s_movk_i32 s75, 0x1600
	s_barrier
	s_mov_b32 s99, 0
	s_branch .LBB0_138

.Lsw1_fused:
	s_setprio 1
	s_barrier
	v_mfma_f32_16x16x32_bf16 v[124:127], v[150:153], v[182:185], 0
	v_exp_f32_e64 v230, -v60
	v_exp_f32_e64 v231, -v61
	v_exp_f32_e64 v232, -v62
	v_exp_f32_e64 v233, -v63
	v_mfma_f32_16x16x32_bf16 v[116:119], v[158:161], v[182:185], 0
	v_exp_f32_e64 v234, -v52
	v_exp_f32_e64 v235, -v53
	v_exp_f32_e64 v236, -v54
	v_exp_f32_e64 v237, -v55
	v_pk_mul_f32 v[56:57], v[60:61], v[56:57]
	v_mfma_f32_16x16x32_bf16 v[108:111], v[150:153], v[190:193], 0
	v_pk_mul_f32 v[58:59], v[62:63], v[58:59]
	v_pk_mul_f32 v[48:49], v[52:53], v[48:49]
	v_pk_mul_f32 v[50:51], v[54:55], v[50:51]
	v_pk_add_f32 v[230:231], v[230:231], 1.0 op_sel_hi:[1,0]
	v_pk_add_f32 v[232:233], v[232:233], 1.0 op_sel_hi:[1,0]
	v_mfma_f32_16x16x32_bf16 v[100:103], v[158:161], v[190:193], 0
	v_pk_add_f32 v[234:235], v[234:235], 1.0 op_sel_hi:[1,0]
	v_pk_add_f32 v[236:237], v[236:237], 1.0 op_sel_hi:[1,0]
	v_rcp_f32_e32 v230, v230
	v_rcp_f32_e32 v231, v231
	v_mfma_f32_16x16x32_bf16 v[92:95], v[150:153], v[198:201], 0
	v_rcp_f32_e32 v232, v232
	v_rcp_f32_e32 v233, v233
	v_rcp_f32_e32 v234, v234
	v_rcp_f32_e32 v235, v235
	v_rcp_f32_e32 v236, v236
	v_mfma_f32_16x16x32_bf16 v[84:87], v[158:161], v[198:201], 0
	v_rcp_f32_e32 v237, v237
	s_add_u32 vcc_lo, s100, 0xb0000
	s_addc_u32 vcc_hi, s101, 0
	v_pk_mul_f32 v[56:57], v[230:231], v[56:57]
	v_pk_mul_f32 v[58:59], v[232:233], v[58:59]
	v_mfma_f32_16x16x32_bf16 v[76:79], v[150:153], v[206:209], 0
	v_pk_mul_f32 v[48:49], v[234:235], v[48:49]
	v_pk_mul_f32 v[50:51], v[236:237], v[50:51]
	v_cvt_pk_bf16_f32 v60, v56, v57
	v_cvt_pk_bf16_f32 v61, v58, v59
	v_mfma_f32_16x16x32_bf16 v[68:71], v[158:161], v[206:209], 0
	v_cvt_pk_bf16_f32 v62, v48, v49
	v_cvt_pk_bf16_f32 v63, v50, v51
	global_store_dwordx4 v224, v[60:63], vcc
	v_exp_f32_e64 v242, -v44
	v_exp_f32_e64 v243, -v45
	v_mfma_f32_16x16x32_bf16 v[124:127], v[154:157], v[186:189], v[124:127]
	v_exp_f32_e64 v244, -v46
	v_exp_f32_e64 v245, -v47
	v_exp_f32_e64 v246, -v36
	v_exp_f32_e64 v247, -v37
	v_exp_f32_e64 v248, -v38
	v_mfma_f32_16x16x32_bf16 v[116:119], v[162:165], v[186:189], v[116:119]
	v_exp_f32_e64 v249, -v39
	v_pk_mul_f32 v[40:41], v[44:45], v[40:41]
	v_pk_mul_f32 v[42:43], v[46:47], v[42:43]
	v_pk_mul_f32 v[32:33], v[36:37], v[32:33]
	v_mfma_f32_16x16x32_bf16 v[108:111], v[154:157], v[194:197], v[108:111]
	v_pk_mul_f32 v[34:35], v[38:39], v[34:35]
	v_pk_add_f32 v[242:243], v[242:243], 1.0 op_sel_hi:[1,0]
	v_pk_add_f32 v[244:245], v[244:245], 1.0 op_sel_hi:[1,0]
	v_pk_add_f32 v[246:247], v[246:247], 1.0 op_sel_hi:[1,0]
	v_pk_add_f32 v[248:249], v[248:249], 1.0 op_sel_hi:[1,0]
	v_mfma_f32_16x16x32_bf16 v[100:103], v[162:165], v[194:197], v[100:103]
	v_rcp_f32_e32 v242, v242
	v_rcp_f32_e32 v243, v243
	v_rcp_f32_e32 v244, v244
	v_rcp_f32_e32 v245, v245
	v_rcp_f32_e32 v246, v246
	v_mfma_f32_16x16x32_bf16 v[92:95], v[154:157], v[202:205], v[92:95]
	v_rcp_f32_e32 v247, v247
	v_rcp_f32_e32 v248, v248
	v_rcp_f32_e32 v249, v249
	s_add_u32 vcc_lo, s100, 0xc6000
	v_mfma_f32_16x16x32_bf16 v[84:87], v[162:165], v[202:205], v[84:87]
	s_addc_u32 vcc_hi, s101, 0
	v_pk_mul_f32 v[40:41], v[242:243], v[40:41]
	v_pk_mul_f32 v[42:43], v[244:245], v[42:43]
	v_pk_mul_f32 v[32:33], v[246:247], v[32:33]
	v_pk_mul_f32 v[34:35], v[248:249], v[34:35]
	v_mfma_f32_16x16x32_bf16 v[76:79], v[154:157], v[210:213], v[76:79]
	v_cvt_pk_bf16_f32 v44, v40, v41
	v_cvt_pk_bf16_f32 v45, v42, v43
	v_cvt_pk_bf16_f32 v46, v32, v33
	v_cvt_pk_bf16_f32 v47, v34, v35
	global_store_dwordx4 v224, v[44:47], vcc
	v_mfma_f32_16x16x32_bf16 v[68:71], v[162:165], v[210:213], v[68:71]
	v_exp_f32_e64 v230, -v28
	v_exp_f32_e64 v231, -v29
	v_exp_f32_e64 v232, -v30
	v_exp_f32_e64 v233, -v31
	v_mfma_f32_16x16x32_bf16 v[120:123], v[166:169], v[182:185], 0
	v_exp_f32_e64 v234, -v20
	v_exp_f32_e64 v235, -v21
	v_exp_f32_e64 v236, -v22
	v_exp_f32_e64 v237, -v23
	v_pk_mul_f32 v[24:25], v[28:29], v[24:25]
	v_mfma_f32_16x16x32_bf16 v[112:115], v[174:177], v[182:185], 0
	v_pk_mul_f32 v[26:27], v[30:31], v[26:27]
	v_pk_mul_f32 v[16:17], v[20:21], v[16:17]
	v_pk_mul_f32 v[18:19], v[22:23], v[18:19]
	v_pk_add_f32 v[230:231], v[230:231], 1.0 op_sel_hi:[1,0]
	v_pk_add_f32 v[232:233], v[232:233], 1.0 op_sel_hi:[1,0]
	v_mfma_f32_16x16x32_bf16 v[104:107], v[166:169], v[190:193], 0
	v_pk_add_f32 v[234:235], v[234:235], 1.0 op_sel_hi:[1,0]
	v_pk_add_f32 v[236:237], v[236:237], 1.0 op_sel_hi:[1,0]
	v_rcp_f32_e32 v230, v230
	v_rcp_f32_e32 v231, v231
	v_mfma_f32_16x16x32_bf16 v[96:99], v[174:177], v[190:193], 0
	v_rcp_f32_e32 v232, v232
	v_rcp_f32_e32 v233, v233
	v_rcp_f32_e32 v234, v234
	v_rcp_f32_e32 v235, v235
	v_rcp_f32_e32 v236, v236
	v_mfma_f32_16x16x32_bf16 v[88:91], v[166:169], v[198:201], 0
	v_rcp_f32_e32 v237, v237
	s_add_u32 vcc_lo, s100, 0xdc000
	s_addc_u32 vcc_hi, s101, 0
	v_pk_mul_f32 v[24:25], v[230:231], v[24:25]
	v_pk_mul_f32 v[26:27], v[232:233], v[26:27]
	v_mfma_f32_16x16x32_bf16 v[80:83], v[174:177], v[198:201], 0
	v_pk_mul_f32 v[16:17], v[234:235], v[16:17]
	v_pk_mul_f32 v[18:19], v[236:237], v[18:19]
	v_cvt_pk_bf16_f32 v28, v24, v25
	v_cvt_pk_bf16_f32 v29, v26, v27
	v_mfma_f32_16x16x32_bf16 v[72:75], v[166:169], v[206:209], 0
	v_cvt_pk_bf16_f32 v30, v16, v17
	v_cvt_pk_bf16_f32 v31, v18, v19
	global_store_dwordx4 v224, v[28:31], vcc
	v_exp_f32_e64 v242, -v12
	v_exp_f32_e64 v243, -v13
	v_mfma_f32_16x16x32_bf16 v[64:67], v[174:177], v[206:209], 0
	v_exp_f32_e64 v244, -v14
	v_exp_f32_e64 v245, -v15
	v_exp_f32_e64 v246, -v4
	v_exp_f32_e64 v247, -v5
	v_exp_f32_e64 v248, -v6
	v_mfma_f32_16x16x32_bf16 v[120:123], v[170:173], v[186:189], v[120:123]
	v_exp_f32_e64 v249, -v7
	v_pk_mul_f32 v[8:9], v[12:13], v[8:9]
	v_pk_mul_f32 v[10:11], v[14:15], v[10:11]
	v_pk_mul_f32 v[0:1], v[4:5], v[0:1]
	v_mfma_f32_16x16x32_bf16 v[112:115], v[178:181], v[186:189], v[112:115]
	v_pk_mul_f32 v[2:3], v[6:7], v[2:3]
	v_pk_add_f32 v[242:243], v[242:243], 1.0 op_sel_hi:[1,0]
	v_pk_add_f32 v[244:245], v[244:245], 1.0 op_sel_hi:[1,0]
	v_pk_add_f32 v[246:247], v[246:247], 1.0 op_sel_hi:[1,0]
	v_pk_add_f32 v[248:249], v[248:249], 1.0 op_sel_hi:[1,0]
	v_mfma_f32_16x16x32_bf16 v[104:107], v[170:173], v[194:197], v[104:107]
	v_rcp_f32_e32 v242, v242
	v_rcp_f32_e32 v243, v243
	v_rcp_f32_e32 v244, v244
	v_rcp_f32_e32 v245, v245
	v_rcp_f32_e32 v246, v246
	v_mfma_f32_16x16x32_bf16 v[96:99], v[178:181], v[194:197], v[96:99]
	v_rcp_f32_e32 v247, v247
	v_rcp_f32_e32 v248, v248
	v_rcp_f32_e32 v249, v249
	s_add_u32 vcc_lo, s100, 0xf2000
	v_mfma_f32_16x16x32_bf16 v[88:91], v[170:173], v[202:205], v[88:91]
	s_addc_u32 vcc_hi, s101, 0
	v_pk_mul_f32 v[8:9], v[242:243], v[8:9]
	v_pk_mul_f32 v[10:11], v[244:245], v[10:11]
	v_pk_mul_f32 v[0:1], v[246:247], v[0:1]
	v_pk_mul_f32 v[2:3], v[248:249], v[2:3]
	v_mfma_f32_16x16x32_bf16 v[80:83], v[178:181], v[202:205], v[80:83]
	v_cvt_pk_bf16_f32 v12, v8, v9
	v_cvt_pk_bf16_f32 v13, v10, v11
	v_cvt_pk_bf16_f32 v14, v0, v1
	v_cvt_pk_bf16_f32 v15, v2, v3
	global_store_dwordx4 v224, v[12:15], vcc
	v_mfma_f32_16x16x32_bf16 v[72:75], v[170:173], v[210:213], v[72:75]
	v_mfma_f32_16x16x32_bf16 v[64:67], v[178:181], v[210:213], v[64:67]
	s_barrier
	s_setprio 0

.LBB0_144:
	s_nop 7
	s_nop 7
	s_lshl_b32 s98, s46, 8
	s_mul_i32 s98, s98, s75
	s_lshl_b32 s100, s76, 8
	s_add_u32 s98, s98, s100
	s_add_u32 s100, s24, s98
	s_addc_u32 s101, s25, 0
	v_mul_u32_u24_e32 v224, s75, v144
	v_lshl_add_u32 v224, v146, 1, v224
	v_exp_f32_e64 v230, -v124
	v_exp_f32_e64 v231, -v125
	v_exp_f32_e64 v232, -v126
	v_exp_f32_e64 v233, -v127
	v_exp_f32_e64 v234, -v116
	v_exp_f32_e64 v235, -v117
	v_exp_f32_e64 v236, -v118
	v_exp_f32_e64 v237, -v119
	v_pk_mul_f32 v[120:121], v[124:125], v[120:121]
	v_pk_mul_f32 v[122:123], v[126:127], v[122:123]
	v_pk_mul_f32 v[112:113], v[116:117], v[112:113]
	v_pk_mul_f32 v[114:115], v[118:119], v[114:115]
	v_pk_add_f32 v[230:231], v[230:231], 1.0 op_sel_hi:[1,0]
	v_pk_add_f32 v[232:233], v[232:233], 1.0 op_sel_hi:[1,0]
	v_pk_add_f32 v[234:235], v[234:235], 1.0 op_sel_hi:[1,0]
	v_pk_add_f32 v[236:237], v[236:237], 1.0 op_sel_hi:[1,0]
	v_rcp_f32_e32 v230, v230
	v_rcp_f32_e32 v231, v231
	v_rcp_f32_e32 v232, v232
	v_rcp_f32_e32 v233, v233
	v_rcp_f32_e32 v234, v234
	v_rcp_f32_e32 v235, v235
	v_rcp_f32_e32 v236, v236
	v_rcp_f32_e32 v237, v237
	s_add_u32 vcc_lo, s100, 0x0
	s_addc_u32 vcc_hi, s101, 0
	v_pk_mul_f32 v[120:121], v[230:231], v[120:121]
	v_pk_mul_f32 v[122:123], v[232:233], v[122:123]
	v_pk_mul_f32 v[112:113], v[234:235], v[112:113]
	v_pk_mul_f32 v[114:115], v[236:237], v[114:115]
	v_cvt_pk_bf16_f32 v124, v120, v121
	v_cvt_pk_bf16_f32 v125, v122, v123
	v_cvt_pk_bf16_f32 v126, v112, v113
	v_cvt_pk_bf16_f32 v127, v114, v115
	global_store_dwordx4 v224, v[124:127], vcc
	v_exp_f32_e64 v242, -v108
	v_exp_f32_e64 v243, -v109
	v_exp_f32_e64 v244, -v110
	v_exp_f32_e64 v245, -v111
	v_exp_f32_e64 v246, -v100
	v_exp_f32_e64 v247, -v101
	v_exp_f32_e64 v248, -v102
	v_exp_f32_e64 v249, -v103
	v_pk_mul_f32 v[104:105], v[108:109], v[104:105]
	v_pk_mul_f32 v[106:107], v[110:111], v[106:107]
	v_pk_mul_f32 v[96:97], v[100:101], v[96:97]
	v_pk_mul_f32 v[98:99], v[102:103], v[98:99]
	v_pk_add_f32 v[242:243], v[242:243], 1.0 op_sel_hi:[1,0]
	v_pk_add_f32 v[244:245], v[244:245], 1.0 op_sel_hi:[1,0]
	v_pk_add_f32 v[246:247], v[246:247], 1.0 op_sel_hi:[1,0]
	v_pk_add_f32 v[248:249], v[248:249], 1.0 op_sel_hi:[1,0]
	v_rcp_f32_e32 v242, v242
	v_rcp_f32_e32 v243, v243
	v_rcp_f32_e32 v244, v244
	v_rcp_f32_e32 v245, v245
	v_rcp_f32_e32 v246, v246
	v_rcp_f32_e32 v247, v247
	v_rcp_f32_e32 v248, v248
	v_rcp_f32_e32 v249, v249
	s_add_u32 vcc_lo, s100, 0x16000
	s_addc_u32 vcc_hi, s101, 0
	v_pk_mul_f32 v[104:105], v[242:243], v[104:105]
	v_pk_mul_f32 v[106:107], v[244:245], v[106:107]
	v_pk_mul_f32 v[96:97], v[246:247], v[96:97]
	v_pk_mul_f32 v[98:99], v[248:249], v[98:99]
	v_cvt_pk_bf16_f32 v108, v104, v105
	v_cvt_pk_bf16_f32 v109, v106, v107
	v_cvt_pk_bf16_f32 v110, v96, v97
	v_cvt_pk_bf16_f32 v111, v98, v99
	global_store_dwordx4 v224, v[108:111], vcc
	v_exp_f32_e64 v230, -v92
	v_exp_f32_e64 v231, -v93
	v_exp_f32_e64 v232, -v94
	v_exp_f32_e64 v233, -v95
	v_exp_f32_e64 v234, -v84
	v_exp_f32_e64 v235, -v85
	v_exp_f32_e64 v236, -v86
	v_exp_f32_e64 v237, -v87
	v_pk_mul_f32 v[88:89], v[92:93], v[88:89]
	v_pk_mul_f32 v[90:91], v[94:95], v[90:91]
	v_pk_mul_f32 v[80:81], v[84:85], v[80:81]
	v_pk_mul_f32 v[82:83], v[86:87], v[82:83]
	v_pk_add_f32 v[230:231], v[230:231], 1.0 op_sel_hi:[1,0]
	v_pk_add_f32 v[232:233], v[232:233], 1.0 op_sel_hi:[1,0]
	v_pk_add_f32 v[234:235], v[234:235], 1.0 op_sel_hi:[1,0]
	v_pk_add_f32 v[236:237], v[236:237], 1.0 op_sel_hi:[1,0]
	v_rcp_f32_e32 v230, v230
	v_rcp_f32_e32 v231, v231
	v_rcp_f32_e32 v232, v232
	v_rcp_f32_e32 v233, v233
	v_rcp_f32_e32 v234, v234
	v_rcp_f32_e32 v235, v235
	v_rcp_f32_e32 v236, v236
	v_rcp_f32_e32 v237, v237
	s_add_u32 vcc_lo, s100, 0x2c000
	s_addc_u32 vcc_hi, s101, 0
	v_pk_mul_f32 v[88:89], v[230:231], v[88:89]
	v_pk_mul_f32 v[90:91], v[232:233], v[90:91]
	v_pk_mul_f32 v[80:81], v[234:235], v[80:81]
	v_pk_mul_f32 v[82:83], v[236:237], v[82:83]
	v_cvt_pk_bf16_f32 v92, v88, v89
	v_cvt_pk_bf16_f32 v93, v90, v91
	v_cvt_pk_bf16_f32 v94, v80, v81
	v_cvt_pk_bf16_f32 v95, v82, v83
	global_store_dwordx4 v224, v[92:95], vcc
	v_exp_f32_e64 v242, -v76
	v_exp_f32_e64 v243, -v77
	v_exp_f32_e64 v244, -v78
	v_exp_f32_e64 v245, -v79
	v_exp_f32_e64 v246, -v68
	v_exp_f32_e64 v247, -v69
	v_exp_f32_e64 v248, -v70
	v_exp_f32_e64 v249, -v71
	v_pk_mul_f32 v[72:73], v[76:77], v[72:73]
	v_pk_mul_f32 v[74:75], v[78:79], v[74:75]
	v_pk_mul_f32 v[64:65], v[68:69], v[64:65]
	v_pk_mul_f32 v[66:67], v[70:71], v[66:67]
	v_pk_add_f32 v[242:243], v[242:243], 1.0 op_sel_hi:[1,0]
	v_pk_add_f32 v[244:245], v[244:245], 1.0 op_sel_hi:[1,0]
	v_pk_add_f32 v[246:247], v[246:247], 1.0 op_sel_hi:[1,0]
	v_pk_add_f32 v[248:249], v[248:249], 1.0 op_sel_hi:[1,0]
	v_rcp_f32_e32 v242, v242
	v_rcp_f32_e32 v243, v243
	v_rcp_f32_e32 v244, v244
	v_rcp_f32_e32 v245, v245
	v_rcp_f32_e32 v246, v246
	v_rcp_f32_e32 v247, v247
	v_rcp_f32_e32 v248, v248
	v_rcp_f32_e32 v249, v249
	s_add_u32 vcc_lo, s100, 0x42000
	s_addc_u32 vcc_hi, s101, 0
	v_pk_mul_f32 v[72:73], v[242:243], v[72:73]
	v_pk_mul_f32 v[74:75], v[244:245], v[74:75]
	v_pk_mul_f32 v[64:65], v[246:247], v[64:65]
	v_pk_mul_f32 v[66:67], v[248:249], v[66:67]
	v_cvt_pk_bf16_f32 v76, v72, v73
	v_cvt_pk_bf16_f32 v77, v74, v75
	v_cvt_pk_bf16_f32 v78, v64, v65
	v_cvt_pk_bf16_f32 v79, v66, v67
	global_store_dwordx4 v224, v[76:79], vcc
	s_mov_b32 s99, 1
	s_andn2_b64 vcc, exec, s[0:1]
	s_mov_b64 s[0:1], -1
	s_cbranch_vccnz .LBB0_137
	s_andn2_b64 vcc, exec, s[8:9]
	s_cbranch_vccnz .LBB0_136
	s_barrier
	s_branch .LBB0_136
.LBB0_147:
	s_cmp_eq_u32 s99, 1
	s_cbranch_scc0 .Lsw1_none
	s_nop 7
	s_nop 7
	v_exp_f32_e64 v230, -v60
	v_exp_f32_e64 v231, -v61
	v_exp_f32_e64 v232, -v62
	v_exp_f32_e64 v233, -v63
	v_exp_f32_e64 v234, -v52
	v_exp_f32_e64 v235, -v53
	v_exp_f32_e64 v236, -v54
	v_exp_f32_e64 v237, -v55
	v_pk_mul_f32 v[56:57], v[60:61], v[56:57]
	v_pk_mul_f32 v[58:59], v[62:63], v[58:59]
	v_pk_mul_f32 v[48:49], v[52:53], v[48:49]
	v_pk_mul_f32 v[50:51], v[54:55], v[50:51]
	v_pk_add_f32 v[230:231], v[230:231], 1.0 op_sel_hi:[1,0]
	v_pk_add_f32 v[232:233], v[232:233], 1.0 op_sel_hi:[1,0]
	v_pk_add_f32 v[234:235], v[234:235], 1.0 op_sel_hi:[1,0]
	v_pk_add_f32 v[236:237], v[236:237], 1.0 op_sel_hi:[1,0]
	v_rcp_f32_e32 v230, v230
	v_rcp_f32_e32 v231, v231
	v_rcp_f32_e32 v232, v232
	v_rcp_f32_e32 v233, v233
	v_rcp_f32_e32 v234, v234
	v_rcp_f32_e32 v235, v235
	v_rcp_f32_e32 v236, v236
	v_rcp_f32_e32 v237, v237
	s_add_u32 vcc_lo, s100, 0xb0000
	s_addc_u32 vcc_hi, s101, 0
	v_pk_mul_f32 v[56:57], v[230:231], v[56:57]
	v_pk_mul_f32 v[58:59], v[232:233], v[58:59]
	v_pk_mul_f32 v[48:49], v[234:235], v[48:49]
	v_pk_mul_f32 v[50:51], v[236:237], v[50:51]
	v_cvt_pk_bf16_f32 v60, v56, v57
	v_cvt_pk_bf16_f32 v61, v58, v59
	v_cvt_pk_bf16_f32 v62, v48, v49
	v_cvt_pk_bf16_f32 v63, v50, v51
	global_store_dwordx4 v224, v[60:63], vcc
	v_exp_f32_e64 v242, -v44
	v_exp_f32_e64 v243, -v45
	v_exp_f32_e64 v244, -v46
	v_exp_f32_e64 v245, -v47
	v_exp_f32_e64 v246, -v36
	v_exp_f32_e64 v247, -v37
	v_exp_f32_e64 v248, -v38
	v_exp_f32_e64 v249, -v39
	v_pk_mul_f32 v[40:41], v[44:45], v[40:41]
	v_pk_mul_f32 v[42:43], v[46:47], v[42:43]
	v_pk_mul_f32 v[32:33], v[36:37], v[32:33]
	v_pk_mul_f32 v[34:35], v[38:39], v[34:35]
	v_pk_add_f32 v[242:243], v[242:243], 1.0 op_sel_hi:[1,0]
	v_pk_add_f32 v[244:245], v[244:245], 1.0 op_sel_hi:[1,0]
	v_pk_add_f32 v[246:247], v[246:247], 1.0 op_sel_hi:[1,0]
	v_pk_add_f32 v[248:249], v[248:249], 1.0 op_sel_hi:[1,0]
	v_rcp_f32_e32 v242, v242
	v_rcp_f32_e32 v243, v243
	v_rcp_f32_e32 v244, v244
	v_rcp_f32_e32 v245, v245
	v_rcp_f32_e32 v246, v246
	v_rcp_f32_e32 v247, v247
	v_rcp_f32_e32 v248, v248
	v_rcp_f32_e32 v249, v249
	s_add_u32 vcc_lo, s100, 0xc6000
	s_addc_u32 vcc_hi, s101, 0
	v_pk_mul_f32 v[40:41], v[242:243], v[40:41]
	v_pk_mul_f32 v[42:43], v[244:245], v[42:43]
	v_pk_mul_f32 v[32:33], v[246:247], v[32:33]
	v_pk_mul_f32 v[34:35], v[248:249], v[34:35]
	v_cvt_pk_bf16_f32 v44, v40, v41
	v_cvt_pk_bf16_f32 v45, v42, v43
	v_cvt_pk_bf16_f32 v46, v32, v33
	v_cvt_pk_bf16_f32 v47, v34, v35
	global_store_dwordx4 v224, v[44:47], vcc
	v_exp_f32_e64 v230, -v28
	v_exp_f32_e64 v231, -v29
	v_exp_f32_e64 v232, -v30
	v_exp_f32_e64 v233, -v31
	v_exp_f32_e64 v234, -v20
	v_exp_f32_e64 v235, -v21
	v_exp_f32_e64 v236, -v22
	v_exp_f32_e64 v237, -v23
	v_pk_mul_f32 v[24:25], v[28:29], v[24:25]
	v_pk_mul_f32 v[26:27], v[30:31], v[26:27]
	v_pk_mul_f32 v[16:17], v[20:21], v[16:17]
	v_pk_mul_f32 v[18:19], v[22:23], v[18:19]
	v_pk_add_f32 v[230:231], v[230:231], 1.0 op_sel_hi:[1,0]
	v_pk_add_f32 v[232:233], v[232:233], 1.0 op_sel_hi:[1,0]
	v_pk_add_f32 v[234:235], v[234:235], 1.0 op_sel_hi:[1,0]
	v_pk_add_f32 v[236:237], v[236:237], 1.0 op_sel_hi:[1,0]
	v_rcp_f32_e32 v230, v230
	v_rcp_f32_e32 v231, v231
	v_rcp_f32_e32 v232, v232
	v_rcp_f32_e32 v233, v233
	v_rcp_f32_e32 v234, v234
	v_rcp_f32_e32 v235, v235
	v_rcp_f32_e32 v236, v236
	v_rcp_f32_e32 v237, v237
	s_add_u32 vcc_lo, s100, 0xdc000
	s_addc_u32 vcc_hi, s101, 0
	v_pk_mul_f32 v[24:25], v[230:231], v[24:25]
	v_pk_mul_f32 v[26:27], v[232:233], v[26:27]
	v_pk_mul_f32 v[16:17], v[234:235], v[16:17]
	v_pk_mul_f32 v[18:19], v[236:237], v[18:19]
	v_cvt_pk_bf16_f32 v28, v24, v25
	v_cvt_pk_bf16_f32 v29, v26, v27
	v_cvt_pk_bf16_f32 v30, v16, v17
	v_cvt_pk_bf16_f32 v31, v18, v19
	global_store_dwordx4 v224, v[28:31], vcc
	v_exp_f32_e64 v242, -v12
	v_exp_f32_e64 v243, -v13
	v_exp_f32_e64 v244, -v14
	v_exp_f32_e64 v245, -v15
	v_exp_f32_e64 v246, -v4
	v_exp_f32_e64 v247, -v5
	v_exp_f32_e64 v248, -v6
	v_exp_f32_e64 v249, -v7
	v_pk_mul_f32 v[8:9], v[12:13], v[8:9]
	v_pk_mul_f32 v[10:11], v[14:15], v[10:11]
	v_pk_mul_f32 v[0:1], v[4:5], v[0:1]
	v_pk_mul_f32 v[2:3], v[6:7], v[2:3]
	v_pk_add_f32 v[242:243], v[242:243], 1.0 op_sel_hi:[1,0]
	v_pk_add_f32 v[244:245], v[244:245], 1.0 op_sel_hi:[1,0]
	v_pk_add_f32 v[246:247], v[246:247], 1.0 op_sel_hi:[1,0]
	v_pk_add_f32 v[248:249], v[248:249], 1.0 op_sel_hi:[1,0]
	v_rcp_f32_e32 v242, v242
	v_rcp_f32_e32 v243, v243
	v_rcp_f32_e32 v244, v244
	v_rcp_f32_e32 v245, v245
	v_rcp_f32_e32 v246, v246
	v_rcp_f32_e32 v247, v247
	v_rcp_f32_e32 v248, v248
	v_rcp_f32_e32 v249, v249
	s_add_u32 vcc_lo, s100, 0xf2000
	s_addc_u32 vcc_hi, s101, 0
	v_pk_mul_f32 v[8:9], v[242:243], v[8:9]
	v_pk_mul_f32 v[10:11], v[244:245], v[10:11]
	v_pk_mul_f32 v[0:1], v[246:247], v[0:1]
	v_pk_mul_f32 v[2:3], v[248:249], v[2:3]
	v_cvt_pk_bf16_f32 v12, v8, v9
	v_cvt_pk_bf16_f32 v13, v10, v11
	v_cvt_pk_bf16_f32 v14, v0, v1
	v_cvt_pk_bf16_f32 v15, v2, v3
	global_store_dwordx4 v224, v[12:15], vcc
	s_mov_b32 s99, 0

.LBB0_751:
	s_lshl_b32 s6, s71, 5
	s_mov_b64 s[14:15], 0x80
	s_and_b32 s18, s6, 0x60
	s_add_i32 m0, s27, 0x18000
	v_lshl_add_u64 v[6:7], v[6:7], 0, s[14:15]
	s_lshl_b32 s16, s5, 13
	s_lshr_b32 s17, s18, 3
	s_waitcnt vmcnt(2)
	s_barrier
	global_load_lds_dwordx4 v[6:7], off
	v_lshl_add_u64 v[4:5], v[4:5], 0, s[14:15]
	s_add_i32 m0, s27, 0x1a000
	s_add_i32 s49, s27, 0x8000
	s_add_i32 s50, s27, 0xa000
	global_load_lds_dwordx4 v[4:5], off
	v_lshl_add_u64 v[0:1], v[0:1], 0, s[14:15]
	s_mov_b32 m0, s49
	s_add_u32 s6, s36, 0x40080
	global_load_lds_dwordx4 v[0:1], off
	v_lshl_add_u64 v[0:1], v[2:3], 0, s[14:15]
	s_mov_b32 m0, s50
	s_addc_u32 s7, s37, 0
	global_load_lds_dwordx4 v[0:1], off
	s_add_i32 m0, s27, 0x1c000
	v_lshl_add_u64 v[0:1], s[6:7], 0, v[132:133]
	global_load_lds_dwordx4 v[0:1], off
	v_lshl_add_u64 v[0:1], s[6:7], 0, v[128:129]
	s_add_i32 m0, s27, 0x1e000
	v_lshrrev_b32_e32 v2, 6, v9
	global_load_lds_dwordx4 v[0:1], off
	v_and_b32_e32 v0, 15, v9
	v_lshlrev_b32_e32 v5, 2, v9
	v_lshl_or_b32 v153, s5, 6, v0
	v_and_b32_e32 v3, 48, v9
	v_lshlrev_b32_e32 v4, 10, v2
	v_lshlrev_b32_e32 v0, 6, v0
	v_and_b32_e32 v5, 32, v5
	v_or_b32_e32 v2, s17, v2
	v_bitop3_b32 v6, v0, v5, v3 bitop3:0x36
	v_or_b32_e32 v0, v0, v3
	v_lshlrev_b32_e32 v2, 10, v2
	v_bitop3_b32 v157, v0, v2, v5 bitop3:0xde
	v_and_b32_e32 v2, 64, v9
	v_xor_b32_e32 v0, 16, v9
	v_add_u32_e32 v2, 64, v2
	v_cmp_lt_i32_e32 vcc, v0, v2
	v_lshrrev_b32_e32 v1, 1, v9
	v_and_b32_e32 v1, 56, v1
	v_cndmask_b32_e32 v0, v9, v0, vcc
	v_lshlrev_b32_e32 v161, 2, v0
	v_xor_b32_e32 v0, 32, v9
	v_cmp_lt_i32_e32 vcc, v0, v2
	v_add_u32_e32 v171, s18, v1
	v_mov_b32_e32 v1, v133
	v_cndmask_b32_e32 v0, v9, v0, vcc
	v_lshlrev_b32_e32 v165, 2, v0
	v_and_b32_e32 v0, 0x70, v9
	v_lshl_add_u64 v[136:137], s[10:11], 0, v[0:1]
	v_lshlrev_b32_e32 v0, 14, v12
	v_and_b32_e32 v0, 0xffff8000, v0
	v_lshl_add_u32 v0, v13, 11, v0
	v_and_b32_e32 v1, 1, v12
	v_lshl_or_b32 v0, v1, 6, v0
	v_lshl_add_u32 v138, v14, 1, v0
	v_lshlrev_b32_e32 v0, 14, v8
	v_and_b32_e32 v0, 0xffff8000, v0
	s_waitcnt vmcnt(6)
	s_cmpk_lt_u32 s3, 0x100
	v_lshl_add_u32 v0, v10, 11, v0
	v_and_b32_e32 v1, 1, v8
	v_or3_b32 v4, v4, s16, v6
	s_cselect_b64 s[16:17], -1, 0
	v_lshl_or_b32 v0, v1, 6, v0
	s_add_i32 s53, 0, 0x10000
	s_add_i32 s54, 0, 0x14000
	s_sext_i32_i16 s56, s4
	s_ashr_i32 s51, s34, 31
	s_mov_b32 s52, s34
	v_mov_b32_e32 v139, v133
	v_lshl_add_u32 v140, v11, 1, v0
	v_mov_b32_e32 v141, v133
	v_mov_b64_e32 v[142:143], 0x1b80
	v_mov_b64_e32 v[144:145], 0x1b7f
	v_add_u32_e32 v172, s53, v157
	v_add_u32_e32 v173, s54, v157
	v_add_u32_e32 v174, 0, v4
	v_mov_b32_e32 v175, 0x358637bd
	s_movk_i32 s55, 0x1600
	s_barrier
	s_mov_b32 s99, 0
	s_branch .LBB0_754

.LBB0_756:
	s_nop 0
	v_cndmask_b32_e64 v253, 0, 1, s[4:5]
	v_cmp_ne_u32_e64 s[6:7], 1, v253
	s_andn2_b64 vcc, exec, s[4:5]
	s_cbranch_vccnz .LBB0_758
	s_mul_hi_i32 s11, s18, 0x66666667
	s_lshr_b32 s19, s11, 31
	s_ashr_i32 s11, s11, 4
	s_add_i32 s11, s11, s19
	s_mul_i32 s11, s11, 40
	s_sub_i32 s11, s18, s11
	s_lshl_b32 s11, s11, 1
	s_sub_i32 s11, s18, s11
	s_add_i32 s18, s11, 39
.LBB0_758:
	s_ashr_i32 s19, s18, 31
	s_lshl_b64 s[20:21], s[18:19], 19
	s_add_u32 s20, s62, s20
	s_addc_u32 s21, s63, s21
	s_and_b64 s[22:23], s[4:5], exec
	s_cselect_b32 s19, s21, s39
	s_cselect_b32 s57, s20, s38
	s_ashr_i32 s11, s10, 31
	s_lshl_b64 s[22:23], s[10:11], 19
	s_add_u32 s22, s40, s22
	s_addc_u32 s23, s41, s23
	s_and_b64 s[4:5], s[4:5], exec
	s_cselect_b32 s11, s23, s37
	s_cselect_b32 s58, s22, s36
	s_add_u32 s4, s38, 0x40080
	s_addc_u32 s5, s39, 0
	s_add_u32 s59, s36, 0x100
	s_addc_u32 s66, s37, 0
	s_mov_b32 s67, -2
	ds_read_b128 v[146:149], v172
	ds_read_b128 v[166:169], v172 offset:1024
	ds_read_b128 v[176:179], v172 offset:2048
	ds_read_b128 v[180:183], v172 offset:3072
	ds_read_b128 v[184:187], v173
	ds_read_b128 v[188:191], v173 offset:1024
	ds_read_b128 v[192:195], v173 offset:2048
	ds_read_b128 v[196:199], v173 offset:3072
	s_add_u32 s36, s4, 0xfffc0080
	s_addc_u32 s37, s5, -1
	s_cmp_eq_u32 s67, 12
	s_cselect_b32 s39, s19, s37
	s_cselect_b32 s38, s57, s36
	s_cselect_b32 s37, s11, s66
	s_cselect_b32 s36, s58, s59
	v_lshl_add_u64 v[150:151], s[4:5], 0, v[138:139]
	s_add_i32 m0, s27, 0xc000
	ds_read_b128 v[200:203], v174
	ds_read_b128 v[204:207], v174 offset:1024
	ds_read_b128 v[208:211], v174 offset:2048
	ds_read_b128 v[212:215], v174 offset:3072
	ds_read_b128 v[216:219], v174 offset:4096
	ds_read_b128 v[220:223], v174 offset:5120
	ds_read_b128 v[224:227], v174 offset:6144
	ds_read_b128 v[230:233], v174 offset:7168
	global_load_lds_dwordx4 v[150:151], off
	v_lshl_add_u64 v[150:151], s[4:5], 0, v[140:141]
	s_add_i32 m0, s27, 0xe000
	s_nop 0
	global_load_lds_dwordx4 v[150:151], off
	s_waitcnt vmcnt(8)
	s_waitcnt lgkmcnt(0)
	s_cmp_eq_u32 s99, 1
	s_cbranch_scc1 .Lsw6_fused
	s_setprio 1
	s_barrier
	v_mfma_f32_16x16x32_bf16 v[124:127], v[146:149], v[200:203], 0
	v_mfma_f32_16x16x32_bf16 v[120:123], v[176:179], v[200:203], 0
	v_mfma_f32_16x16x32_bf16 v[108:111], v[146:149], v[208:211], 0
	v_mfma_f32_16x16x32_bf16 v[104:107], v[176:179], v[208:211], 0
	v_mfma_f32_16x16x32_bf16 v[92:95], v[146:149], v[216:219], 0
	v_mfma_f32_16x16x32_bf16 v[88:91], v[176:179], v[216:219], 0
	v_mfma_f32_16x16x32_bf16 v[76:79], v[146:149], v[224:227], 0
	v_mfma_f32_16x16x32_bf16 v[72:75], v[176:179], v[224:227], 0
	v_mfma_f32_16x16x32_bf16 v[124:127], v[166:169], v[204:207], v[124:127]
	v_mfma_f32_16x16x32_bf16 v[120:123], v[180:183], v[204:207], v[120:123]
	v_mfma_f32_16x16x32_bf16 v[108:111], v[166:169], v[212:215], v[108:111]
	v_mfma_f32_16x16x32_bf16 v[104:107], v[180:183], v[212:215], v[104:107]
	v_mfma_f32_16x16x32_bf16 v[92:95], v[166:169], v[220:223], v[92:95]
	v_mfma_f32_16x16x32_bf16 v[88:91], v[180:183], v[220:223], v[88:91]
	v_mfma_f32_16x16x32_bf16 v[76:79], v[166:169], v[230:233], v[76:79]
	v_mfma_f32_16x16x32_bf16 v[72:75], v[180:183], v[230:233], v[72:75]
	v_mfma_f32_16x16x32_bf16 v[116:119], v[184:187], v[200:203], 0
	v_mfma_f32_16x16x32_bf16 v[112:115], v[192:195], v[200:203], 0
	v_mfma_f32_16x16x32_bf16 v[100:103], v[184:187], v[208:211], 0
	v_mfma_f32_16x16x32_bf16 v[96:99], v[192:195], v[208:211], 0
	v_mfma_f32_16x16x32_bf16 v[84:87], v[184:187], v[216:219], 0
	v_mfma_f32_16x16x32_bf16 v[80:83], v[192:195], v[216:219], 0
	v_mfma_f32_16x16x32_bf16 v[68:71], v[184:187], v[224:227], 0
	v_mfma_f32_16x16x32_bf16 v[64:67], v[192:195], v[224:227], 0
	v_mfma_f32_16x16x32_bf16 v[116:119], v[188:191], v[204:207], v[116:119]
	v_mfma_f32_16x16x32_bf16 v[112:115], v[196:199], v[204:207], v[112:115]
	v_mfma_f32_16x16x32_bf16 v[100:103], v[188:191], v[212:215], v[100:103]
	v_mfma_f32_16x16x32_bf16 v[96:99], v[196:199], v[212:215], v[96:99]
	v_mfma_f32_16x16x32_bf16 v[84:87], v[188:191], v[220:223], v[84:87]
	v_mfma_f32_16x16x32_bf16 v[80:83], v[196:199], v[220:223], v[80:83]
	v_mfma_f32_16x16x32_bf16 v[68:71], v[188:191], v[230:233], v[68:71]
	v_mfma_f32_16x16x32_bf16 v[64:67], v[196:199], v[230:233], v[64:67]
	s_barrier
	s_setprio 0
	s_branch .Lsw6_join
.Lsw6_fused:
	s_setprio 1
	s_barrier
	v_mfma_f32_16x16x32_bf16 v[124:127], v[146:149], v[200:203], 0
	v_exp_f32_e64 v236, -v60
	v_exp_f32_e64 v237, -v61
	v_exp_f32_e64 v238, -v62
	v_exp_f32_e64 v239, -v63
	v_mfma_f32_16x16x32_bf16 v[120:123], v[176:179], v[200:203], 0
	v_exp_f32_e64 v240, -v56
	v_exp_f32_e64 v241, -v57
	v_exp_f32_e64 v242, -v58
	v_exp_f32_e64 v243, -v59
	v_pk_mul_f32 v[52:53], v[60:61], v[52:53]
	v_mfma_f32_16x16x32_bf16 v[108:111], v[146:149], v[208:211], 0
	v_pk_mul_f32 v[54:55], v[62:63], v[54:55]
	v_pk_mul_f32 v[48:49], v[56:57], v[48:49]
	v_pk_mul_f32 v[50:51], v[58:59], v[50:51]
	v_pk_add_f32 v[236:237], v[236:237], 1.0 op_sel_hi:[1,0]
	v_pk_add_f32 v[238:239], v[238:239], 1.0 op_sel_hi:[1,0]
	v_mfma_f32_16x16x32_bf16 v[104:107], v[176:179], v[208:211], 0
	v_pk_add_f32 v[240:241], v[240:241], 1.0 op_sel_hi:[1,0]
	v_pk_add_f32 v[242:243], v[242:243], 1.0 op_sel_hi:[1,0]
	v_rcp_f32_e32 v236, v236
	v_rcp_f32_e32 v237, v237
	v_mfma_f32_16x16x32_bf16 v[92:95], v[146:149], v[216:219], 0
	v_rcp_f32_e32 v238, v238
	v_rcp_f32_e32 v239, v239
	v_rcp_f32_e32 v240, v240
	v_rcp_f32_e32 v241, v241
	v_rcp_f32_e32 v242, v242
	v_mfma_f32_16x16x32_bf16 v[88:91], v[176:179], v[216:219], 0
	v_rcp_f32_e32 v243, v243
	s_add_u32 vcc_lo, s100, 0xb0000
	s_addc_u32 vcc_hi, s101, 0
	v_pk_mul_f32 v[52:53], v[236:237], v[52:53]
	v_pk_mul_f32 v[54:55], v[238:239], v[54:55]
	v_mfma_f32_16x16x32_bf16 v[76:79], v[146:149], v[224:227], 0
	v_pk_mul_f32 v[48:49], v[240:241], v[48:49]
	v_pk_mul_f32 v[50:51], v[242:243], v[50:51]
	v_cvt_pk_bf16_f32 v60, v52, v53
	v_cvt_pk_bf16_f32 v61, v54, v55
	v_mfma_f32_16x16x32_bf16 v[72:75], v[176:179], v[224:227], 0
	v_cvt_pk_bf16_f32 v62, v48, v49
	v_cvt_pk_bf16_f32 v63, v50, v51
	global_store_dwordx4 v229, v[60:63], vcc
	v_exp_f32_e64 v244, -v44
	v_exp_f32_e64 v245, -v45
	v_mfma_f32_16x16x32_bf16 v[124:127], v[166:169], v[204:207], v[124:127]
	v_exp_f32_e64 v246, -v46
	v_exp_f32_e64 v247, -v47
	v_exp_f32_e64 v248, -v40
	v_exp_f32_e64 v249, -v41
	v_exp_f32_e64 v250, -v42
	v_mfma_f32_16x16x32_bf16 v[120:123], v[180:183], v[204:207], v[120:123]
	v_exp_f32_e64 v251, -v43
	v_pk_mul_f32 v[36:37], v[44:45], v[36:37]
	v_pk_mul_f32 v[38:39], v[46:47], v[38:39]
	v_pk_mul_f32 v[32:33], v[40:41], v[32:33]
	v_mfma_f32_16x16x32_bf16 v[108:111], v[166:169], v[212:215], v[108:111]
	v_pk_mul_f32 v[34:35], v[42:43], v[34:35]
	v_pk_add_f32 v[244:245], v[244:245], 1.0 op_sel_hi:[1,0]
	v_pk_add_f32 v[246:247], v[246:247], 1.0 op_sel_hi:[1,0]
	v_pk_add_f32 v[248:249], v[248:249], 1.0 op_sel_hi:[1,0]
	v_pk_add_f32 v[250:251], v[250:251], 1.0 op_sel_hi:[1,0]
	v_mfma_f32_16x16x32_bf16 v[104:107], v[180:183], v[212:215], v[104:107]
	v_rcp_f32_e32 v244, v244
	v_rcp_f32_e32 v245, v245
	v_rcp_f32_e32 v246, v246
	v_rcp_f32_e32 v247, v247
	v_rcp_f32_e32 v248, v248
	v_mfma_f32_16x16x32_bf16 v[92:95], v[166:169], v[220:223], v[92:95]
	v_rcp_f32_e32 v249, v249
	v_rcp_f32_e32 v250, v250
	v_rcp_f32_e32 v251, v251
	s_add_u32 vcc_lo, s100, 0xc6000
	v_mfma_f32_16x16x32_bf16 v[88:91], v[180:183], v[220:223], v[88:91]
	s_addc_u32 vcc_hi, s101, 0
	v_pk_mul_f32 v[36:37], v[244:245], v[36:37]
	v_pk_mul_f32 v[38:39], v[246:247], v[38:39]
	v_pk_mul_f32 v[32:33], v[248:249], v[32:33]
	v_pk_mul_f32 v[34:35], v[250:251], v[34:35]
	v_mfma_f32_16x16x32_bf16 v[76:79], v[166:169], v[230:233], v[76:79]
	v_cvt_pk_bf16_f32 v44, v36, v37
	v_cvt_pk_bf16_f32 v45, v38, v39
	v_cvt_pk_bf16_f32 v46, v32, v33
	v_cvt_pk_bf16_f32 v47, v34, v35
	global_store_dwordx4 v229, v[44:47], vcc
	v_mfma_f32_16x16x32_bf16 v[72:75], v[180:183], v[230:233], v[72:75]
	v_exp_f32_e64 v236, -v28
	v_exp_f32_e64 v237, -v29
	v_exp_f32_e64 v238, -v30
	v_exp_f32_e64 v239, -v31
	v_mfma_f32_16x16x32_bf16 v[116:119], v[184:187], v[200:203], 0
	v_exp_f32_e64 v240, -v24
	v_exp_f32_e64 v241, -v25
	v_exp_f32_e64 v242, -v26
	v_exp_f32_e64 v243, -v27
	v_pk_mul_f32 v[20:21], v[28:29], v[20:21]
	v_mfma_f32_16x16x32_bf16 v[112:115], v[192:195], v[200:203], 0
	v_pk_mul_f32 v[22:23], v[30:31], v[22:23]
	v_pk_mul_f32 v[16:17], v[24:25], v[16:17]
	v_pk_mul_f32 v[18:19], v[26:27], v[18:19]
	v_pk_add_f32 v[236:237], v[236:237], 1.0 op_sel_hi:[1,0]
	v_pk_add_f32 v[238:239], v[238:239], 1.0 op_sel_hi:[1,0]
	v_mfma_f32_16x16x32_bf16 v[100:103], v[184:187], v[208:211], 0
	v_pk_add_f32 v[240:241], v[240:241], 1.0 op_sel_hi:[1,0]
	v_pk_add_f32 v[242:243], v[242:243], 1.0 op_sel_hi:[1,0]
	v_rcp_f32_e32 v236, v236
	v_rcp_f32_e32 v237, v237
	v_mfma_f32_16x16x32_bf16 v[96:99], v[192:195], v[208:211], 0
	v_rcp_f32_e32 v238, v238
	v_rcp_f32_e32 v239, v239
	v_rcp_f32_e32 v240, v240
	v_rcp_f32_e32 v241, v241
	v_rcp_f32_e32 v242, v242
	v_mfma_f32_16x16x32_bf16 v[84:87], v[184:187], v[216:219], 0
	v_rcp_f32_e32 v243, v243
	s_add_u32 vcc_lo, s100, 0xdc000
	s_addc_u32 vcc_hi, s101, 0
	v_pk_mul_f32 v[20:21], v[236:237], v[20:21]
	v_pk_mul_f32 v[22:23], v[238:239], v[22:23]
	v_mfma_f32_16x16x32_bf16 v[80:83], v[192:195], v[216:219], 0
	v_pk_mul_f32 v[16:17], v[240:241], v[16:17]
	v_pk_mul_f32 v[18:19], v[242:243], v[18:19]
	v_cvt_pk_bf16_f32 v28, v20, v21
	v_cvt_pk_bf16_f32 v29, v22, v23
	v_mfma_f32_16x16x32_bf16 v[68:71], v[184:187], v[224:227], 0
	v_cvt_pk_bf16_f32 v30, v16, v17
	v_cvt_pk_bf16_f32 v31, v18, v19
	global_store_dwordx4 v229, v[28:31], vcc
	v_exp_f32_e64 v244, -v12
	v_exp_f32_e64 v245, -v13
	v_mfma_f32_16x16x32_bf16 v[64:67], v[192:195], v[224:227], 0
	v_exp_f32_e64 v246, -v14
	v_exp_f32_e64 v247, -v15
	v_exp_f32_e64 v248, -v8
	v_exp_f32_e64 v249, -v9
	v_exp_f32_e64 v250, -v10
	v_mfma_f32_16x16x32_bf16 v[116:119], v[188:191], v[204:207], v[116:119]
	v_exp_f32_e64 v251, -v11
	v_pk_mul_f32 v[4:5], v[12:13], v[4:5]
	v_pk_mul_f32 v[6:7], v[14:15], v[6:7]
	v_pk_mul_f32 v[0:1], v[8:9], v[0:1]
	v_mfma_f32_16x16x32_bf16 v[112:115], v[196:199], v[204:207], v[112:115]
	v_pk_mul_f32 v[2:3], v[10:11], v[2:3]
	v_pk_add_f32 v[244:245], v[244:245], 1.0 op_sel_hi:[1,0]
	v_pk_add_f32 v[246:247], v[246:247], 1.0 op_sel_hi:[1,0]
	v_pk_add_f32 v[248:249], v[248:249], 1.0 op_sel_hi:[1,0]
	v_pk_add_f32 v[250:251], v[250:251], 1.0 op_sel_hi:[1,0]
	v_mfma_f32_16x16x32_bf16 v[100:103], v[188:191], v[212:215], v[100:103]
	v_rcp_f32_e32 v244, v244
	v_rcp_f32_e32 v245, v245
	v_rcp_f32_e32 v246, v246
	v_rcp_f32_e32 v247, v247
	v_rcp_f32_e32 v248, v248
	v_mfma_f32_16x16x32_bf16 v[96:99], v[196:199], v[212:215], v[96:99]
	v_rcp_f32_e32 v249, v249
	v_rcp_f32_e32 v250, v250
	v_rcp_f32_e32 v251, v251
	s_add_u32 vcc_lo, s100, 0xf2000
	v_mfma_f32_16x16x32_bf16 v[84:87], v[188:191], v[220:223], v[84:87]
	s_addc_u32 vcc_hi, s101, 0
	v_pk_mul_f32 v[4:5], v[244:245], v[4:5]
	v_pk_mul_f32 v[6:7], v[246:247], v[6:7]
	v_pk_mul_f32 v[0:1], v[248:249], v[0:1]
	v_pk_mul_f32 v[2:3], v[250:251], v[2:3]
	v_mfma_f32_16x16x32_bf16 v[80:83], v[196:199], v[220:223], v[80:83]
	v_cvt_pk_bf16_f32 v12, v4, v5
	v_cvt_pk_bf16_f32 v13, v6, v7
	v_cvt_pk_bf16_f32 v14, v0, v1
	v_cvt_pk_bf16_f32 v15, v2, v3
	global_store_dwordx4 v229, v[12:15], vcc
	v_mfma_f32_16x16x32_bf16 v[68:71], v[188:191], v[230:233], v[68:71]
	v_mfma_f32_16x16x32_bf16 v[64:67], v[196:199], v[230:233], v[64:67]
	s_barrier
	s_setprio 0
.Lsw6_join:
	s_add_i32 s68, s53, s42
	v_lshl_add_u64 v[150:151], s[36:37], 0, v[132:133]
	s_mov_b32 m0, s68
	ds_read_b128 v[200:203], v174 offset:16384
	ds_read_b128 v[204:207], v174 offset:17408
	ds_read_b128 v[208:211], v174 offset:18432
	ds_read_b128 v[212:215], v174 offset:19456
	ds_read_b128 v[216:219], v174 offset:20480
	ds_read_b128 v[220:223], v174 offset:21504
	ds_read_b128 v[224:227], v174 offset:22528
	ds_read_b128 v[230:233], v174 offset:23552
	global_load_lds_dwordx4 v[150:151], off
	s_add_i32 m0, s68, 0x2000
	s_add_u32 s68, s36, 0x40000
	v_lshl_add_u64 v[154:155], s[36:37], 0, v[128:129]
	s_addc_u32 s69, s37, 0
	s_add_i32 s70, s54, s42
	global_load_lds_dwordx4 v[154:155], off
	v_lshl_add_u64 v[158:159], s[68:69], 0, v[132:133]
	s_mov_b32 m0, s70
	v_lshl_add_u64 v[162:163], s[38:39], 0, v[130:131]
	global_load_lds_dwordx4 v[158:159], off
	v_lshl_add_u64 v[158:159], s[68:69], 0, v[128:129]
	s_add_i32 m0, s70, 0x2000
	s_nop 0
	global_load_lds_dwordx4 v[158:159], off
	v_lshl_add_u64 v[158:159], s[38:39], 0, v[134:135]
	s_mov_b32 m0, s27
	s_nop 0
	global_load_lds_dwordx4 v[158:159], off
	s_mov_b32 m0, s45
	s_nop 0
	global_load_lds_dwordx4 v[162:163], off
	s_waitcnt vmcnt(8)
	s_waitcnt lgkmcnt(0)
	s_setprio 1
	s_barrier
	v_mfma_f32_16x16x32_bf16 v[60:63], v[146:149], v[200:203], 0
	v_mfma_f32_16x16x32_bf16 v[56:59], v[176:179], v[200:203], 0
	v_mfma_f32_16x16x32_bf16 v[44:47], v[146:149], v[208:211], 0
	v_mfma_f32_16x16x32_bf16 v[40:43], v[176:179], v[208:211], 0
	v_mfma_f32_16x16x32_bf16 v[28:31], v[146:149], v[216:219], 0
	v_mfma_f32_16x16x32_bf16 v[24:27], v[176:179], v[216:219], 0
	v_mfma_f32_16x16x32_bf16 v[12:15], v[146:149], v[224:227], 0
	v_mfma_f32_16x16x32_bf16 v[8:11], v[176:179], v[224:227], 0
	v_mfma_f32_16x16x32_bf16 v[60:63], v[166:169], v[204:207], v[60:63]
	v_mfma_f32_16x16x32_bf16 v[56:59], v[180:183], v[204:207], v[56:59]
	v_mfma_f32_16x16x32_bf16 v[44:47], v[166:169], v[212:215], v[44:47]
	v_mfma_f32_16x16x32_bf16 v[40:43], v[180:183], v[212:215], v[40:43]
	v_mfma_f32_16x16x32_bf16 v[28:31], v[166:169], v[220:223], v[28:31]
	v_mfma_f32_16x16x32_bf16 v[24:27], v[180:183], v[220:223], v[24:27]
	v_mfma_f32_16x16x32_bf16 v[12:15], v[166:169], v[230:233], v[12:15]
	v_mfma_f32_16x16x32_bf16 v[8:11], v[180:183], v[230:233], v[8:11]
	v_mfma_f32_16x16x32_bf16 v[52:55], v[184:187], v[200:203], 0
	v_mfma_f32_16x16x32_bf16 v[48:51], v[192:195], v[200:203], 0
	v_mfma_f32_16x16x32_bf16 v[36:39], v[184:187], v[208:211], 0
	v_mfma_f32_16x16x32_bf16 v[32:35], v[192:195], v[208:211], 0
	v_mfma_f32_16x16x32_bf16 v[20:23], v[184:187], v[216:219], 0
	v_mfma_f32_16x16x32_bf16 v[16:19], v[192:195], v[216:219], 0
	v_mfma_f32_16x16x32_bf16 v[4:7], v[184:187], v[224:227], 0
	v_mfma_f32_16x16x32_bf16 v[0:3], v[192:195], v[224:227], 0
	v_mfma_f32_16x16x32_bf16 v[52:55], v[188:191], v[204:207], v[52:55]
	v_mfma_f32_16x16x32_bf16 v[48:51], v[196:199], v[204:207], v[48:51]
	v_mfma_f32_16x16x32_bf16 v[36:39], v[188:191], v[212:215], v[36:39]
	v_mfma_f32_16x16x32_bf16 v[32:35], v[196:199], v[212:215], v[32:35]
	v_mfma_f32_16x16x32_bf16 v[20:23], v[188:191], v[220:223], v[20:23]
	v_mfma_f32_16x16x32_bf16 v[16:19], v[196:199], v[220:223], v[16:19]
	v_mfma_f32_16x16x32_bf16 v[4:7], v[188:191], v[230:233], v[4:7]
	v_mfma_f32_16x16x32_bf16 v[0:3], v[196:199], v[230:233], v[0:3]
	s_barrier
	s_setprio 0
	s_add_i32 s68, 0, 0x18000
	v_add_u32_e32 v152, s68, v157
	s_add_i32 s69, 0, 0x1c000
	ds_read_b128 v[146:149], v152
	ds_read_b128 v[166:169], v152 offset:1024
	ds_read_b128 v[176:179], v152 offset:2048
	ds_read_b128 v[180:183], v152 offset:3072
	v_add_u32_e32 v152, s69, v157
	ds_read_b128 v[184:187], v152
	ds_read_b128 v[188:191], v152 offset:1024
	ds_read_b128 v[192:195], v152 offset:2048
	ds_read_b128 v[196:199], v152 offset:3072
	s_add_u32 s38, s38, 0x40000
	s_addc_u32 s39, s39, 0
	s_mov_b32 m0, s46
	v_lshl_add_u64 v[234:235], s[38:39], 0, v[134:135]
	ds_read_b128 v[200:203], v174 offset:32768
	ds_read_b128 v[204:207], v174 offset:33792
	ds_read_b128 v[208:211], v174 offset:34816
	ds_read_b128 v[212:215], v174 offset:35840
	ds_read_b128 v[216:219], v174 offset:36864
	ds_read_b128 v[220:223], v174 offset:37888
	ds_read_b128 v[224:227], v174 offset:38912
	ds_read_b128 v[230:233], v174 offset:39936
	global_load_lds_dwordx4 v[234:235], off
	v_lshl_add_u64 v[234:235], s[38:39], 0, v[130:131]
	s_mov_b32 m0, s47
	s_nop 0
	global_load_lds_dwordx4 v[234:235], off
	s_waitcnt vmcnt(8)
	s_waitcnt lgkmcnt(0)
	s_setprio 1
	s_barrier
	v_mfma_f32_16x16x32_bf16 v[124:127], v[146:149], v[200:203], v[124:127]
	v_mfma_f32_16x16x32_bf16 v[120:123], v[176:179], v[200:203], v[120:123]
	v_mfma_f32_16x16x32_bf16 v[108:111], v[146:149], v[208:211], v[108:111]
	v_mfma_f32_16x16x32_bf16 v[104:107], v[176:179], v[208:211], v[104:107]
	v_mfma_f32_16x16x32_bf16 v[92:95], v[146:149], v[216:219], v[92:95]
	v_mfma_f32_16x16x32_bf16 v[88:91], v[176:179], v[216:219], v[88:91]
	v_mfma_f32_16x16x32_bf16 v[76:79], v[146:149], v[224:227], v[76:79]
	v_mfma_f32_16x16x32_bf16 v[72:75], v[176:179], v[224:227], v[72:75]
	v_mfma_f32_16x16x32_bf16 v[124:127], v[166:169], v[204:207], v[124:127]
	v_mfma_f32_16x16x32_bf16 v[120:123], v[180:183], v[204:207], v[120:123]
	v_mfma_f32_16x16x32_bf16 v[108:111], v[166:169], v[212:215], v[108:111]
	v_mfma_f32_16x16x32_bf16 v[104:107], v[180:183], v[212:215], v[104:107]
	v_mfma_f32_16x16x32_bf16 v[92:95], v[166:169], v[220:223], v[92:95]
	v_mfma_f32_16x16x32_bf16 v[88:91], v[180:183], v[220:223], v[88:91]
	v_mfma_f32_16x16x32_bf16 v[76:79], v[166:169], v[230:233], v[76:79]
	v_mfma_f32_16x16x32_bf16 v[72:75], v[180:183], v[230:233], v[72:75]
	v_mfma_f32_16x16x32_bf16 v[116:119], v[184:187], v[200:203], v[116:119]
	v_mfma_f32_16x16x32_bf16 v[112:115], v[192:195], v[200:203], v[112:115]
	v_mfma_f32_16x16x32_bf16 v[100:103], v[184:187], v[208:211], v[100:103]
	v_mfma_f32_16x16x32_bf16 v[96:99], v[192:195], v[208:211], v[96:99]
	v_mfma_f32_16x16x32_bf16 v[84:87], v[184:187], v[216:219], v[84:87]
	v_mfma_f32_16x16x32_bf16 v[80:83], v[192:195], v[216:219], v[80:83]
	v_mfma_f32_16x16x32_bf16 v[68:71], v[184:187], v[224:227], v[68:71]
	v_mfma_f32_16x16x32_bf16 v[64:67], v[192:195], v[224:227], v[64:67]
	v_mfma_f32_16x16x32_bf16 v[116:119], v[188:191], v[204:207], v[116:119]
	v_mfma_f32_16x16x32_bf16 v[112:115], v[196:199], v[204:207], v[112:115]
	v_mfma_f32_16x16x32_bf16 v[100:103], v[188:191], v[212:215], v[100:103]
	v_mfma_f32_16x16x32_bf16 v[96:99], v[196:199], v[212:215], v[96:99]
	v_mfma_f32_16x16x32_bf16 v[84:87], v[188:191], v[220:223], v[84:87]
	v_mfma_f32_16x16x32_bf16 v[80:83], v[196:199], v[220:223], v[80:83]
	v_mfma_f32_16x16x32_bf16 v[68:71], v[188:191], v[230:233], v[68:71]
	v_mfma_f32_16x16x32_bf16 v[64:67], v[196:199], v[230:233], v[64:67]
	s_barrier
	s_setprio 0
	s_add_i32 s38, s68, s42
	v_lshl_add_u64 v[150:151], v[150:151], 0, s[14:15]
	s_mov_b32 m0, s38
	ds_read_b128 v[200:203], v174 offset:49152
	ds_read_b128 v[204:207], v174 offset:50176
	ds_read_b128 v[208:211], v174 offset:51200
	ds_read_b128 v[212:215], v174 offset:52224
	ds_read_b128 v[216:219], v174 offset:53248
	ds_read_b128 v[220:223], v174 offset:54272
	ds_read_b128 v[224:227], v174 offset:55296
	ds_read_b128 v[230:233], v174 offset:56320
	global_load_lds_dwordx4 v[150:151], off
	s_add_i32 m0, s38, 0x2000
	s_add_u32 s36, s36, 0x40080
	v_lshl_add_u64 v[150:151], v[154:155], 0, s[14:15]
	s_addc_u32 s37, s37, 0
	s_add_i32 s38, s69, s42
	global_load_lds_dwordx4 v[150:151], off
	v_lshl_add_u64 v[150:151], s[36:37], 0, v[132:133]
	s_mov_b32 m0, s38
	s_nop 0
	global_load_lds_dwordx4 v[150:151], off
	v_lshl_add_u64 v[150:151], s[36:37], 0, v[128:129]
	s_add_i32 m0, s38, 0x2000
	s_nop 0
	global_load_lds_dwordx4 v[150:151], off
	v_lshl_add_u64 v[150:151], v[158:159], 0, s[14:15]
	s_mov_b32 m0, s49
	s_nop 0
	global_load_lds_dwordx4 v[150:151], off
	v_lshl_add_u64 v[150:151], v[162:163], 0, s[14:15]
	s_mov_b32 m0, s50
	s_nop 0
	global_load_lds_dwordx4 v[150:151], off
	s_waitcnt vmcnt(8)
	s_waitcnt lgkmcnt(0)
	s_setprio 1
	s_barrier
	v_mfma_f32_16x16x32_bf16 v[60:63], v[146:149], v[200:203], v[60:63]
	v_mfma_f32_16x16x32_bf16 v[56:59], v[176:179], v[200:203], v[56:59]
	v_mfma_f32_16x16x32_bf16 v[44:47], v[146:149], v[208:211], v[44:47]
	v_mfma_f32_16x16x32_bf16 v[40:43], v[176:179], v[208:211], v[40:43]
	v_mfma_f32_16x16x32_bf16 v[28:31], v[146:149], v[216:219], v[28:31]
	v_mfma_f32_16x16x32_bf16 v[24:27], v[176:179], v[216:219], v[24:27]
	v_mfma_f32_16x16x32_bf16 v[12:15], v[146:149], v[224:227], v[12:15]
	v_mfma_f32_16x16x32_bf16 v[8:11], v[176:179], v[224:227], v[8:11]
	v_mfma_f32_16x16x32_bf16 v[60:63], v[166:169], v[204:207], v[60:63]
	v_mfma_f32_16x16x32_bf16 v[56:59], v[180:183], v[204:207], v[56:59]
	v_mfma_f32_16x16x32_bf16 v[44:47], v[166:169], v[212:215], v[44:47]
	v_mfma_f32_16x16x32_bf16 v[40:43], v[180:183], v[212:215], v[40:43]
	v_mfma_f32_16x16x32_bf16 v[28:31], v[166:169], v[220:223], v[28:31]
	v_mfma_f32_16x16x32_bf16 v[24:27], v[180:183], v[220:223], v[24:27]
	v_mfma_f32_16x16x32_bf16 v[12:15], v[166:169], v[230:233], v[12:15]
	v_mfma_f32_16x16x32_bf16 v[8:11], v[180:183], v[230:233], v[8:11]
	v_mfma_f32_16x16x32_bf16 v[52:55], v[184:187], v[200:203], v[52:55]
	v_mfma_f32_16x16x32_bf16 v[48:51], v[192:195], v[200:203], v[48:51]
	v_mfma_f32_16x16x32_bf16 v[36:39], v[184:187], v[208:211], v[36:39]
	v_mfma_f32_16x16x32_bf16 v[32:35], v[192:195], v[208:211], v[32:35]
	v_mfma_f32_16x16x32_bf16 v[20:23], v[184:187], v[216:219], v[20:23]
	v_mfma_f32_16x16x32_bf16 v[16:19], v[192:195], v[216:219], v[16:19]
	v_mfma_f32_16x16x32_bf16 v[4:7], v[184:187], v[224:227], v[4:7]
	v_mfma_f32_16x16x32_bf16 v[0:3], v[192:195], v[224:227], v[0:3]
	v_mfma_f32_16x16x32_bf16 v[52:55], v[188:191], v[204:207], v[52:55]
	v_mfma_f32_16x16x32_bf16 v[48:51], v[196:199], v[204:207], v[48:51]
	v_mfma_f32_16x16x32_bf16 v[36:39], v[188:191], v[212:215], v[36:39]
	v_mfma_f32_16x16x32_bf16 v[32:35], v[196:199], v[212:215], v[32:35]
	v_mfma_f32_16x16x32_bf16 v[20:23], v[188:191], v[220:223], v[20:23]
	v_mfma_f32_16x16x32_bf16 v[16:19], v[196:199], v[220:223], v[16:19]
	v_mfma_f32_16x16x32_bf16 v[4:7], v[188:191], v[230:233], v[4:7]
	v_mfma_f32_16x16x32_bf16 v[0:3], v[196:199], v[230:233], v[0:3]
	s_barrier
	s_setprio 0
	s_add_i32 s67, s67, 2
	s_add_u32 s4, s4, 0x100
	s_addc_u32 s5, s5, 0
	s_add_u32 s59, s59, 0x100
	s_addc_u32 s66, s66, 0
	s_cmp_gt_u32 s67, 13

.LBB0_762:
	s_mul_i32 s98, s26, 0x667
	s_lshr_b32 s98, s98, 16
	s_mul_i32 s98, s98, 40
	s_sub_u32 s98, s26, s98
	s_lshr_b32 s98, s98, 3
	s_lshl_b32 s98, s98, 10
	s_add_u32 s98, s98, 0x20800
	v_mov_b32_e32 v179, v153
	v_lshl_add_u32 v179, v179, 2, s98
	ds_read_b32 v147, v179 offset:0
	ds_read_b32 v149, v179 offset:128
	ds_read_b32 v151, v179 offset:64
	ds_read_b32 v155, v179 offset:512
	ds_read_b32 v159, v179 offset:192
	ds_read_b32 v163, v179 offset:576
	ds_read_b32 v167, v179 offset:640
	ds_read_b32 v169, v179 offset:704
	s_waitcnt lgkmcnt(0)
	s_nop 7
	s_nop 7
	s_lshl_b32 s98, s26, 8
	s_mul_i32 s98, s98, s55
	s_lshl_b32 s100, s56, 8
	s_add_u32 s98, s98, s100
	s_add_u32 s100, s24, s98
	s_addc_u32 s101, s25, 0
	v_mul_u32_u24_e32 v229, s55, v153
	v_lshl_add_u32 v229, v171, 1, v229
	v_mov_b32_e32 v236, v155
	v_pk_mul_f32 v[60:61], v[60:61], v[236:237] op_sel_hi:[1,0]
	v_pk_mul_f32 v[62:63], v[62:63], v[236:237] op_sel_hi:[1,0]
	v_pk_mul_f32 v[56:57], v[56:57], v[236:237] op_sel_hi:[1,0]
	v_pk_mul_f32 v[58:59], v[58:59], v[236:237] op_sel_hi:[1,0]
	v_pk_mul_f32 v[52:53], v[52:53], v[236:237] op_sel_hi:[1,0]
	v_pk_mul_f32 v[54:55], v[54:55], v[236:237] op_sel_hi:[1,0]
	v_pk_mul_f32 v[48:49], v[48:49], v[236:237] op_sel_hi:[1,0]
	v_pk_mul_f32 v[50:51], v[50:51], v[236:237] op_sel_hi:[1,0]
	v_mov_b32_e32 v244, v163
	v_pk_mul_f32 v[44:45], v[44:45], v[244:245] op_sel_hi:[1,0]
	v_pk_mul_f32 v[46:47], v[46:47], v[244:245] op_sel_hi:[1,0]
	v_pk_mul_f32 v[40:41], v[40:41], v[244:245] op_sel_hi:[1,0]
	v_pk_mul_f32 v[42:43], v[42:43], v[244:245] op_sel_hi:[1,0]
	v_pk_mul_f32 v[36:37], v[36:37], v[244:245] op_sel_hi:[1,0]
	v_pk_mul_f32 v[38:39], v[38:39], v[244:245] op_sel_hi:[1,0]
	v_pk_mul_f32 v[32:33], v[32:33], v[244:245] op_sel_hi:[1,0]
	v_pk_mul_f32 v[34:35], v[34:35], v[244:245] op_sel_hi:[1,0]
	v_mov_b32_e32 v236, v167
	v_pk_mul_f32 v[28:29], v[28:29], v[236:237] op_sel_hi:[1,0]
	v_pk_mul_f32 v[30:31], v[30:31], v[236:237] op_sel_hi:[1,0]
	v_pk_mul_f32 v[24:25], v[24:25], v[236:237] op_sel_hi:[1,0]
	v_pk_mul_f32 v[26:27], v[26:27], v[236:237] op_sel_hi:[1,0]
	v_pk_mul_f32 v[20:21], v[20:21], v[236:237] op_sel_hi:[1,0]
	v_pk_mul_f32 v[22:23], v[22:23], v[236:237] op_sel_hi:[1,0]
	v_pk_mul_f32 v[16:17], v[16:17], v[236:237] op_sel_hi:[1,0]
	v_pk_mul_f32 v[18:19], v[18:19], v[236:237] op_sel_hi:[1,0]
	v_mov_b32_e32 v244, v169
	v_pk_mul_f32 v[12:13], v[12:13], v[244:245] op_sel_hi:[1,0]
	v_pk_mul_f32 v[14:15], v[14:15], v[244:245] op_sel_hi:[1,0]
	v_pk_mul_f32 v[8:9], v[8:9], v[244:245] op_sel_hi:[1,0]
	v_pk_mul_f32 v[10:11], v[10:11], v[244:245] op_sel_hi:[1,0]
	v_pk_mul_f32 v[4:5], v[4:5], v[244:245] op_sel_hi:[1,0]
	v_pk_mul_f32 v[6:7], v[6:7], v[244:245] op_sel_hi:[1,0]
	v_pk_mul_f32 v[0:1], v[0:1], v[244:245] op_sel_hi:[1,0]
	v_pk_mul_f32 v[2:3], v[2:3], v[244:245] op_sel_hi:[1,0]
	v_mov_b32_e32 v236, v147
	v_pk_mul_f32 v[124:125], v[124:125], v[236:237] op_sel_hi:[1,0]
	v_pk_mul_f32 v[126:127], v[126:127], v[236:237] op_sel_hi:[1,0]
	v_pk_mul_f32 v[120:121], v[120:121], v[236:237] op_sel_hi:[1,0]
	v_pk_mul_f32 v[122:123], v[122:123], v[236:237] op_sel_hi:[1,0]
	v_pk_mul_f32 v[116:117], v[116:117], v[236:237] op_sel_hi:[1,0]
	v_pk_mul_f32 v[118:119], v[118:119], v[236:237] op_sel_hi:[1,0]
	v_pk_mul_f32 v[112:113], v[112:113], v[236:237] op_sel_hi:[1,0]
	v_pk_mul_f32 v[114:115], v[114:115], v[236:237] op_sel_hi:[1,0]
	v_exp_f32_e64 v236, -v124
	v_exp_f32_e64 v237, -v125
	v_exp_f32_e64 v238, -v126
	v_exp_f32_e64 v239, -v127
	v_exp_f32_e64 v240, -v120
	v_exp_f32_e64 v241, -v121
	v_exp_f32_e64 v242, -v122
	v_exp_f32_e64 v243, -v123
	v_pk_mul_f32 v[116:117], v[124:125], v[116:117]
	v_pk_mul_f32 v[118:119], v[126:127], v[118:119]
	v_pk_mul_f32 v[112:113], v[120:121], v[112:113]
	v_pk_mul_f32 v[114:115], v[122:123], v[114:115]
	v_pk_add_f32 v[236:237], v[236:237], 1.0 op_sel_hi:[1,0]
	v_pk_add_f32 v[238:239], v[238:239], 1.0 op_sel_hi:[1,0]
	v_pk_add_f32 v[240:241], v[240:241], 1.0 op_sel_hi:[1,0]
	v_pk_add_f32 v[242:243], v[242:243], 1.0 op_sel_hi:[1,0]
	v_rcp_f32_e32 v236, v236
	v_rcp_f32_e32 v237, v237
	v_rcp_f32_e32 v238, v238
	v_rcp_f32_e32 v239, v239
	v_rcp_f32_e32 v240, v240
	v_rcp_f32_e32 v241, v241
	v_rcp_f32_e32 v242, v242
	v_rcp_f32_e32 v243, v243
	s_add_u32 vcc_lo, s100, 0x0
	s_addc_u32 vcc_hi, s101, 0
	v_pk_mul_f32 v[116:117], v[236:237], v[116:117]
	v_pk_mul_f32 v[118:119], v[238:239], v[118:119]
	v_pk_mul_f32 v[112:113], v[240:241], v[112:113]
	v_pk_mul_f32 v[114:115], v[242:243], v[114:115]
	v_cvt_pk_bf16_f32 v124, v116, v117
	v_cvt_pk_bf16_f32 v125, v118, v119
	v_cvt_pk_bf16_f32 v126, v112, v113
	v_cvt_pk_bf16_f32 v127, v114, v115
	global_store_dwordx4 v229, v[124:127], vcc
	v_mov_b32_e32 v244, v151
	v_pk_mul_f32 v[108:109], v[108:109], v[244:245] op_sel_hi:[1,0]
	v_pk_mul_f32 v[110:111], v[110:111], v[244:245] op_sel_hi:[1,0]
	v_pk_mul_f32 v[104:105], v[104:105], v[244:245] op_sel_hi:[1,0]
	v_pk_mul_f32 v[106:107], v[106:107], v[244:245] op_sel_hi:[1,0]
	v_pk_mul_f32 v[100:101], v[100:101], v[244:245] op_sel_hi:[1,0]
	v_pk_mul_f32 v[102:103], v[102:103], v[244:245] op_sel_hi:[1,0]
	v_pk_mul_f32 v[96:97], v[96:97], v[244:245] op_sel_hi:[1,0]
	v_pk_mul_f32 v[98:99], v[98:99], v[244:245] op_sel_hi:[1,0]
	v_exp_f32_e64 v244, -v108
	v_exp_f32_e64 v245, -v109
	v_exp_f32_e64 v246, -v110
	v_exp_f32_e64 v247, -v111
	v_exp_f32_e64 v248, -v104
	v_exp_f32_e64 v249, -v105
	v_exp_f32_e64 v250, -v106
	v_exp_f32_e64 v251, -v107
	v_pk_mul_f32 v[100:101], v[108:109], v[100:101]
	v_pk_mul_f32 v[102:103], v[110:111], v[102:103]
	v_pk_mul_f32 v[96:97], v[104:105], v[96:97]
	v_pk_mul_f32 v[98:99], v[106:107], v[98:99]
	v_pk_add_f32 v[244:245], v[244:245], 1.0 op_sel_hi:[1,0]
	v_pk_add_f32 v[246:247], v[246:247], 1.0 op_sel_hi:[1,0]
	v_pk_add_f32 v[248:249], v[248:249], 1.0 op_sel_hi:[1,0]
	v_pk_add_f32 v[250:251], v[250:251], 1.0 op_sel_hi:[1,0]
	v_rcp_f32_e32 v244, v244
	v_rcp_f32_e32 v245, v245
	v_rcp_f32_e32 v246, v246
	v_rcp_f32_e32 v247, v247
	v_rcp_f32_e32 v248, v248
	v_rcp_f32_e32 v249, v249
	v_rcp_f32_e32 v250, v250
	v_rcp_f32_e32 v251, v251
	s_add_u32 vcc_lo, s100, 0x16000
	s_addc_u32 vcc_hi, s101, 0
	v_pk_mul_f32 v[100:101], v[244:245], v[100:101]
	v_pk_mul_f32 v[102:103], v[246:247], v[102:103]
	v_pk_mul_f32 v[96:97], v[248:249], v[96:97]
	v_pk_mul_f32 v[98:99], v[250:251], v[98:99]
	v_cvt_pk_bf16_f32 v108, v100, v101
	v_cvt_pk_bf16_f32 v109, v102, v103
	v_cvt_pk_bf16_f32 v110, v96, v97
	v_cvt_pk_bf16_f32 v111, v98, v99
	global_store_dwordx4 v229, v[108:111], vcc
	v_mov_b32_e32 v236, v149
	v_pk_mul_f32 v[92:93], v[92:93], v[236:237] op_sel_hi:[1,0]
	v_pk_mul_f32 v[94:95], v[94:95], v[236:237] op_sel_hi:[1,0]
	v_pk_mul_f32 v[88:89], v[88:89], v[236:237] op_sel_hi:[1,0]
	v_pk_mul_f32 v[90:91], v[90:91], v[236:237] op_sel_hi:[1,0]
	v_pk_mul_f32 v[84:85], v[84:85], v[236:237] op_sel_hi:[1,0]
	v_pk_mul_f32 v[86:87], v[86:87], v[236:237] op_sel_hi:[1,0]
	v_pk_mul_f32 v[80:81], v[80:81], v[236:237] op_sel_hi:[1,0]
	v_pk_mul_f32 v[82:83], v[82:83], v[236:237] op_sel_hi:[1,0]
	v_exp_f32_e64 v236, -v92
	v_exp_f32_e64 v237, -v93
	v_exp_f32_e64 v238, -v94
	v_exp_f32_e64 v239, -v95
	v_exp_f32_e64 v240, -v88
	v_exp_f32_e64 v241, -v89
	v_exp_f32_e64 v242, -v90
	v_exp_f32_e64 v243, -v91
	v_pk_mul_f32 v[84:85], v[92:93], v[84:85]
	v_pk_mul_f32 v[86:87], v[94:95], v[86:87]
	v_pk_mul_f32 v[80:81], v[88:89], v[80:81]
	v_pk_mul_f32 v[82:83], v[90:91], v[82:83]
	v_pk_add_f32 v[236:237], v[236:237], 1.0 op_sel_hi:[1,0]
	v_pk_add_f32 v[238:239], v[238:239], 1.0 op_sel_hi:[1,0]
	v_pk_add_f32 v[240:241], v[240:241], 1.0 op_sel_hi:[1,0]
	v_pk_add_f32 v[242:243], v[242:243], 1.0 op_sel_hi:[1,0]
	v_rcp_f32_e32 v236, v236
	v_rcp_f32_e32 v237, v237
	v_rcp_f32_e32 v238, v238
	v_rcp_f32_e32 v239, v239
	v_rcp_f32_e32 v240, v240
	v_rcp_f32_e32 v241, v241
	v_rcp_f32_e32 v242, v242
	v_rcp_f32_e32 v243, v243
	s_add_u32 vcc_lo, s100, 0x2c000
	s_addc_u32 vcc_hi, s101, 0
	v_pk_mul_f32 v[84:85], v[236:237], v[84:85]
	v_pk_mul_f32 v[86:87], v[238:239], v[86:87]
	v_pk_mul_f32 v[80:81], v[240:241], v[80:81]
	v_pk_mul_f32 v[82:83], v[242:243], v[82:83]
	v_cvt_pk_bf16_f32 v92, v84, v85
	v_cvt_pk_bf16_f32 v93, v86, v87
	v_cvt_pk_bf16_f32 v94, v80, v81
	v_cvt_pk_bf16_f32 v95, v82, v83
	global_store_dwordx4 v229, v[92:95], vcc
	v_mov_b32_e32 v244, v159
	v_pk_mul_f32 v[76:77], v[76:77], v[244:245] op_sel_hi:[1,0]
	v_pk_mul_f32 v[78:79], v[78:79], v[244:245] op_sel_hi:[1,0]
	v_pk_mul_f32 v[72:73], v[72:73], v[244:245] op_sel_hi:[1,0]
	v_pk_mul_f32 v[74:75], v[74:75], v[244:245] op_sel_hi:[1,0]
	v_pk_mul_f32 v[68:69], v[68:69], v[244:245] op_sel_hi:[1,0]
	v_pk_mul_f32 v[70:71], v[70:71], v[244:245] op_sel_hi:[1,0]
	v_pk_mul_f32 v[64:65], v[64:65], v[244:245] op_sel_hi:[1,0]
	v_pk_mul_f32 v[66:67], v[66:67], v[244:245] op_sel_hi:[1,0]
	v_exp_f32_e64 v244, -v76
	v_exp_f32_e64 v245, -v77
	v_exp_f32_e64 v246, -v78
	v_exp_f32_e64 v247, -v79
	v_exp_f32_e64 v248, -v72
	v_exp_f32_e64 v249, -v73
	v_exp_f32_e64 v250, -v74
	v_exp_f32_e64 v251, -v75
	v_pk_mul_f32 v[68:69], v[76:77], v[68:69]
	v_pk_mul_f32 v[70:71], v[78:79], v[70:71]
	v_pk_mul_f32 v[64:65], v[72:73], v[64:65]
	v_pk_mul_f32 v[66:67], v[74:75], v[66:67]
	v_pk_add_f32 v[244:245], v[244:245], 1.0 op_sel_hi:[1,0]
	v_pk_add_f32 v[246:247], v[246:247], 1.0 op_sel_hi:[1,0]
	v_pk_add_f32 v[248:249], v[248:249], 1.0 op_sel_hi:[1,0]
	v_pk_add_f32 v[250:251], v[250:251], 1.0 op_sel_hi:[1,0]
	v_rcp_f32_e32 v244, v244
	v_rcp_f32_e32 v245, v245
	v_rcp_f32_e32 v246, v246
	v_rcp_f32_e32 v247, v247
	v_rcp_f32_e32 v248, v248
	v_rcp_f32_e32 v249, v249
	v_rcp_f32_e32 v250, v250
	v_rcp_f32_e32 v251, v251
	s_add_u32 vcc_lo, s100, 0x42000
	s_addc_u32 vcc_hi, s101, 0
	v_pk_mul_f32 v[68:69], v[244:245], v[68:69]
	v_pk_mul_f32 v[70:71], v[246:247], v[70:71]
	v_pk_mul_f32 v[64:65], v[248:249], v[64:65]
	v_pk_mul_f32 v[66:67], v[250:251], v[66:67]
	v_cvt_pk_bf16_f32 v76, v68, v69
	v_cvt_pk_bf16_f32 v77, v70, v71
	v_cvt_pk_bf16_f32 v78, v64, v65
	v_cvt_pk_bf16_f32 v79, v66, v67
	global_store_dwordx4 v229, v[76:79], vcc
	s_mov_b32 s99, 1
	s_and_b64 vcc, exec, s[6:7]
	s_mov_b64 s[4:5], -1
	s_cbranch_vccnz .LBB0_753
	s_andn2_b64 vcc, exec, s[12:13]
	s_cbranch_vccnz .LBB0_752
	s_barrier
	s_branch .LBB0_752
.LBB0_765:
	s_cmp_eq_u32 s99, 1
	s_cbranch_scc0 .Lsw6_none
	s_nop 7
	s_nop 7
	v_exp_f32_e64 v236, -v60
	v_exp_f32_e64 v237, -v61
	v_exp_f32_e64 v238, -v62
	v_exp_f32_e64 v239, -v63
	v_exp_f32_e64 v240, -v56
	v_exp_f32_e64 v241, -v57
	v_exp_f32_e64 v242, -v58
	v_exp_f32_e64 v243, -v59
	v_pk_mul_f32 v[52:53], v[60:61], v[52:53]
	v_pk_mul_f32 v[54:55], v[62:63], v[54:55]
	v_pk_mul_f32 v[48:49], v[56:57], v[48:49]
	v_pk_mul_f32 v[50:51], v[58:59], v[50:51]
	v_pk_add_f32 v[236:237], v[236:237], 1.0 op_sel_hi:[1,0]
	v_pk_add_f32 v[238:239], v[238:239], 1.0 op_sel_hi:[1,0]
	v_pk_add_f32 v[240:241], v[240:241], 1.0 op_sel_hi:[1,0]
	v_pk_add_f32 v[242:243], v[242:243], 1.0 op_sel_hi:[1,0]
	v_rcp_f32_e32 v236, v236
	v_rcp_f32_e32 v237, v237
	v_rcp_f32_e32 v238, v238
	v_rcp_f32_e32 v239, v239
	v_rcp_f32_e32 v240, v240
	v_rcp_f32_e32 v241, v241
	v_rcp_f32_e32 v242, v242
	v_rcp_f32_e32 v243, v243
	s_add_u32 vcc_lo, s100, 0xb0000
	s_addc_u32 vcc_hi, s101, 0
	v_pk_mul_f32 v[52:53], v[236:237], v[52:53]
	v_pk_mul_f32 v[54:55], v[238:239], v[54:55]
	v_pk_mul_f32 v[48:49], v[240:241], v[48:49]
	v_pk_mul_f32 v[50:51], v[242:243], v[50:51]
	v_cvt_pk_bf16_f32 v60, v52, v53
	v_cvt_pk_bf16_f32 v61, v54, v55
	v_cvt_pk_bf16_f32 v62, v48, v49
	v_cvt_pk_bf16_f32 v63, v50, v51
	global_store_dwordx4 v229, v[60:63], vcc
	v_exp_f32_e64 v244, -v44
	v_exp_f32_e64 v245, -v45
	v_exp_f32_e64 v246, -v46
	v_exp_f32_e64 v247, -v47
	v_exp_f32_e64 v248, -v40
	v_exp_f32_e64 v249, -v41
	v_exp_f32_e64 v250, -v42
	v_exp_f32_e64 v251, -v43
	v_pk_mul_f32 v[36:37], v[44:45], v[36:37]
	v_pk_mul_f32 v[38:39], v[46:47], v[38:39]
	v_pk_mul_f32 v[32:33], v[40:41], v[32:33]
	v_pk_mul_f32 v[34:35], v[42:43], v[34:35]
	v_pk_add_f32 v[244:245], v[244:245], 1.0 op_sel_hi:[1,0]
	v_pk_add_f32 v[246:247], v[246:247], 1.0 op_sel_hi:[1,0]
	v_pk_add_f32 v[248:249], v[248:249], 1.0 op_sel_hi:[1,0]
	v_pk_add_f32 v[250:251], v[250:251], 1.0 op_sel_hi:[1,0]
	v_rcp_f32_e32 v244, v244
	v_rcp_f32_e32 v245, v245
	v_rcp_f32_e32 v246, v246
	v_rcp_f32_e32 v247, v247
	v_rcp_f32_e32 v248, v248
	v_rcp_f32_e32 v249, v249
	v_rcp_f32_e32 v250, v250
	v_rcp_f32_e32 v251, v251
	s_add_u32 vcc_lo, s100, 0xc6000
	s_addc_u32 vcc_hi, s101, 0
	v_pk_mul_f32 v[36:37], v[244:245], v[36:37]
	v_pk_mul_f32 v[38:39], v[246:247], v[38:39]
	v_pk_mul_f32 v[32:33], v[248:249], v[32:33]
	v_pk_mul_f32 v[34:35], v[250:251], v[34:35]
	v_cvt_pk_bf16_f32 v44, v36, v37
	v_cvt_pk_bf16_f32 v45, v38, v39
	v_cvt_pk_bf16_f32 v46, v32, v33
	v_cvt_pk_bf16_f32 v47, v34, v35
	global_store_dwordx4 v229, v[44:47], vcc
	v_exp_f32_e64 v236, -v28
	v_exp_f32_e64 v237, -v29
	v_exp_f32_e64 v238, -v30
	v_exp_f32_e64 v239, -v31
	v_exp_f32_e64 v240, -v24
	v_exp_f32_e64 v241, -v25
	v_exp_f32_e64 v242, -v26
	v_exp_f32_e64 v243, -v27
	v_pk_mul_f32 v[20:21], v[28:29], v[20:21]
	v_pk_mul_f32 v[22:23], v[30:31], v[22:23]
	v_pk_mul_f32 v[16:17], v[24:25], v[16:17]
	v_pk_mul_f32 v[18:19], v[26:27], v[18:19]
	v_pk_add_f32 v[236:237], v[236:237], 1.0 op_sel_hi:[1,0]
	v_pk_add_f32 v[238:239], v[238:239], 1.0 op_sel_hi:[1,0]
	v_pk_add_f32 v[240:241], v[240:241], 1.0 op_sel_hi:[1,0]
	v_pk_add_f32 v[242:243], v[242:243], 1.0 op_sel_hi:[1,0]
	v_rcp_f32_e32 v236, v236
	v_rcp_f32_e32 v237, v237
	v_rcp_f32_e32 v238, v238
	v_rcp_f32_e32 v239, v239
	v_rcp_f32_e32 v240, v240
	v_rcp_f32_e32 v241, v241
	v_rcp_f32_e32 v242, v242
	v_rcp_f32_e32 v243, v243
	s_add_u32 vcc_lo, s100, 0xdc000
	s_addc_u32 vcc_hi, s101, 0
	v_pk_mul_f32 v[20:21], v[236:237], v[20:21]
	v_pk_mul_f32 v[22:23], v[238:239], v[22:23]
	v_pk_mul_f32 v[16:17], v[240:241], v[16:17]
	v_pk_mul_f32 v[18:19], v[242:243], v[18:19]
	v_cvt_pk_bf16_f32 v28, v20, v21
	v_cvt_pk_bf16_f32 v29, v22, v23
	v_cvt_pk_bf16_f32 v30, v16, v17
	v_cvt_pk_bf16_f32 v31, v18, v19
	global_store_dwordx4 v229, v[28:31], vcc
	v_exp_f32_e64 v244, -v12
	v_exp_f32_e64 v245, -v13
	v_exp_f32_e64 v246, -v14
	v_exp_f32_e64 v247, -v15
	v_exp_f32_e64 v248, -v8
	v_exp_f32_e64 v249, -v9
	v_exp_f32_e64 v250, -v10
	v_exp_f32_e64 v251, -v11
	v_pk_mul_f32 v[4:5], v[12:13], v[4:5]
	v_pk_mul_f32 v[6:7], v[14:15], v[6:7]
	v_pk_mul_f32 v[0:1], v[8:9], v[0:1]
	v_pk_mul_f32 v[2:3], v[10:11], v[2:3]
	v_pk_add_f32 v[244:245], v[244:245], 1.0 op_sel_hi:[1,0]
	v_pk_add_f32 v[246:247], v[246:247], 1.0 op_sel_hi:[1,0]
	v_pk_add_f32 v[248:249], v[248:249], 1.0 op_sel_hi:[1,0]
	v_pk_add_f32 v[250:251], v[250:251], 1.0 op_sel_hi:[1,0]
	v_rcp_f32_e32 v244, v244
	v_rcp_f32_e32 v245, v245
	v_rcp_f32_e32 v246, v246
	v_rcp_f32_e32 v247, v247
	v_rcp_f32_e32 v248, v248
	v_rcp_f32_e32 v249, v249
	v_rcp_f32_e32 v250, v250
	v_rcp_f32_e32 v251, v251
	s_add_u32 vcc_lo, s100, 0xf2000
	s_addc_u32 vcc_hi, s101, 0
	v_pk_mul_f32 v[4:5], v[244:245], v[4:5]
	v_pk_mul_f32 v[6:7], v[246:247], v[6:7]
	v_pk_mul_f32 v[0:1], v[248:249], v[0:1]
	v_pk_mul_f32 v[2:3], v[250:251], v[2:3]
	v_cvt_pk_bf16_f32 v12, v4, v5
	v_cvt_pk_bf16_f32 v13, v6, v7
	v_cvt_pk_bf16_f32 v14, v0, v1
	v_cvt_pk_bf16_f32 v15, v2, v3
	global_store_dwordx4 v229, v[12:15], vcc
	s_mov_b32 s99, 0
